# padded bias table + ds_read2 near path; rotated cb64 tile sweep for L2 reuse; P4 epilogue pair-pipelined 8 loads in flight
# baseline (speedup 1.0000x reference)
;     __device__ __forceinline__ void operator()(AccRef acc, const pg8::Unit& u, int wr, int wc, int fr, int fq) const {
;         const int row0 = u.pm * 256 + wr * 64 + fr, col0 = u.pn * 256 + wc * 64 + fq * 8;
;         const float* xb = (u.pm >= 128) ? xs - (size_t)MP * 1024 : xp;
; #pragma unroll
;         for (int ai = 0; ai < 2; ++ai)
; #pragma unroll
;             for (int m = 0; m < 4; ++m) { const size_t off = (size_t)(row0 + ai * 128 + m * 16) * 1024 + col0;
; #pragma unroll
;                 for (int bj = 0; bj < 2; ++bj) { const f32x4 x0 = __builtin_nontemporal_load((const f32x4*)(xb + off + bj * 32)), x1 = __builtin_nontemporal_load((const f32x4*)(xb + off + bj * 32 + 4));
;                     __builtin_nontemporal_store(x0 + acc[ai][bj][m][0], (f32x4*)(out + off + bj * 32)); __builtin_nontemporal_store(x1 + acc[ai][bj][m][1], (f32x4*)(out + off + bj * 32 + 4)); } }
.LBB0_606:
	v_lshl_add_u32 v138, s26, 8, v140
	v_lshl_or_b32 v139, s27, 8, v142
	s_cmpk_gt_i32 s26, 0x7f
	s_cselect_b32 s27, s48, s65
	s_cselect_b32 s26, s45, s64
	s_andn2_b64 vcc, exec, s[20:21]
	s_mov_b64 s[20:21], -1
	v_lshl_add_u32 v138, v138, 10, v139
	v_lshlrev_b32_e32 v138, 2, v138
	v_mov_b32_e32 v139, v138
	global_load_dwordx4 v[146:149], v139, s[26:27] nt
	global_load_dwordx4 v[150:153], v139, s[26:27] offset:16 nt
	v_mov_b32_e32 v139, v138
	global_load_dwordx4 v[154:157], v139, s[26:27] offset:128 nt
	global_load_dwordx4 v[158:161], v139, s[26:27] offset:144 nt
	v_add_u32_e32 v139, 0x10000, v138
	global_load_dwordx4 v[162:165], v139, s[26:27] nt
	global_load_dwordx4 v[166:169], v139, s[26:27] offset:16 nt
	v_add_u32_e32 v139, 0x10000, v138
	global_load_dwordx4 v[170:173], v139, s[26:27] offset:128 nt
	global_load_dwordx4 v[174:177], v139, s[26:27] offset:144 nt
	s_waitcnt vmcnt(6)
	v_pk_add_f32 v[124:125], v[124:125], v[146:147]
	v_pk_add_f32 v[126:127], v[126:127], v[148:149]
	v_pk_add_f32 v[120:121], v[120:121], v[150:151]
	v_pk_add_f32 v[122:123], v[122:123], v[152:153]
	v_mov_b32_e32 v139, v138
	global_store_dwordx4 v139, v[124:127], s[60:61] nt
	global_store_dwordx4 v139, v[120:123], s[60:61] offset:16 nt
	v_add_u32_e32 v139, 0x20000, v138
	global_load_dwordx4 v[146:149], v139, s[26:27] nt
	global_load_dwordx4 v[150:153], v139, s[26:27] offset:16 nt
	s_waitcnt vmcnt(8)
	v_pk_add_f32 v[112:113], v[112:113], v[154:155]
	v_pk_add_f32 v[114:115], v[114:115], v[156:157]
	v_pk_add_f32 v[108:109], v[108:109], v[158:159]
	v_pk_add_f32 v[110:111], v[110:111], v[160:161]
	v_mov_b32_e32 v139, v138
	global_store_dwordx4 v139, v[112:115], s[60:61] offset:128 nt
	global_store_dwordx4 v139, v[108:111], s[60:61] offset:144 nt
	v_add_u32_e32 v139, 0x20000, v138
	global_load_dwordx4 v[154:157], v139, s[26:27] offset:128 nt
	global_load_dwordx4 v[158:161], v139, s[26:27] offset:144 nt
	s_waitcnt vmcnt(10)
	v_pk_add_f32 v[116:117], v[116:117], v[162:163]
	v_pk_add_f32 v[118:119], v[118:119], v[164:165]
	v_pk_add_f32 v[104:105], v[104:105], v[166:167]
	v_pk_add_f32 v[106:107], v[106:107], v[168:169]
	v_add_u32_e32 v139, 0x10000, v138
	global_store_dwordx4 v139, v[116:119], s[60:61] nt
	global_store_dwordx4 v139, v[104:107], s[60:61] offset:16 nt
	v_add_u32_e32 v139, 0x30000, v138
	global_load_dwordx4 v[162:165], v139, s[26:27] nt
	global_load_dwordx4 v[166:169], v139, s[26:27] offset:16 nt
	s_waitcnt vmcnt(12)
	v_pk_add_f32 v[96:97], v[96:97], v[170:171]
	v_pk_add_f32 v[98:99], v[98:99], v[172:173]
	v_pk_add_f32 v[92:93], v[92:93], v[174:175]
	v_pk_add_f32 v[94:95], v[94:95], v[176:177]
	v_add_u32_e32 v139, 0x10000, v138
	global_store_dwordx4 v139, v[96:99], s[60:61] offset:128 nt
	global_store_dwordx4 v139, v[92:95], s[60:61] offset:144 nt
	v_add_u32_e32 v139, 0x30000, v138
	global_load_dwordx4 v[170:173], v139, s[26:27] offset:128 nt
	global_load_dwordx4 v[174:177], v139, s[26:27] offset:144 nt
	s_waitcnt vmcnt(12)
	v_pk_add_f32 v[100:101], v[100:101], v[146:147]
	v_pk_add_f32 v[102:103], v[102:103], v[148:149]
	v_pk_add_f32 v[88:89], v[88:89], v[150:151]
	v_pk_add_f32 v[90:91], v[90:91], v[152:153]
	v_add_u32_e32 v139, 0x20000, v138
	global_store_dwordx4 v139, v[100:103], s[60:61] nt
	global_store_dwordx4 v139, v[88:91], s[60:61] offset:16 nt
	v_add_u32_e32 v139, 0x80000, v138
	global_load_dwordx4 v[146:149], v139, s[26:27] nt
	global_load_dwordx4 v[150:153], v139, s[26:27] offset:16 nt
	s_waitcnt vmcnt(12)
	v_pk_add_f32 v[80:81], v[80:81], v[154:155]
	v_pk_add_f32 v[82:83], v[82:83], v[156:157]
	v_pk_add_f32 v[76:77], v[76:77], v[158:159]
	v_pk_add_f32 v[78:79], v[78:79], v[160:161]
	v_add_u32_e32 v139, 0x20000, v138
	global_store_dwordx4 v139, v[80:83], s[60:61] offset:128 nt
	global_store_dwordx4 v139, v[76:79], s[60:61] offset:144 nt
	v_add_u32_e32 v139, 0x80000, v138
	global_load_dwordx4 v[154:157], v139, s[26:27] offset:128 nt
	global_load_dwordx4 v[158:161], v139, s[26:27] offset:144 nt
	s_waitcnt vmcnt(12)
	v_pk_add_f32 v[84:85], v[84:85], v[162:163]
	v_pk_add_f32 v[86:87], v[86:87], v[164:165]
	v_pk_add_f32 v[72:73], v[72:73], v[166:167]
	v_pk_add_f32 v[74:75], v[74:75], v[168:169]
	v_add_u32_e32 v139, 0x30000, v138
	global_store_dwordx4 v139, v[84:87], s[60:61] nt
	global_store_dwordx4 v139, v[72:75], s[60:61] offset:16 nt
	v_add_u32_e32 v139, 0x90000, v138
	global_load_dwordx4 v[162:165], v139, s[26:27] nt
	global_load_dwordx4 v[166:169], v139, s[26:27] offset:16 nt
	s_waitcnt vmcnt(12)
; #define PG8_BAR __builtin_amdgcn_s_barrier()
; template <class Epi, class Sched>
; __device__ __forceinline__ void gemm_phase(LAS unsigned char* lds, const Gemm g, const Sched& S, const Epi& E) {
;     ...
;         if (!has_next) break;
; #pragma unroll
;         for (int a = 0; a < 2; ++a)
; #pragma unroll
;             for (int b = 0; b < 2; ++b)
; #pragma unroll
;                 for (int m = 0; m < 4; ++m)
; #pragma unroll
;                     for (int n = 0; n < 2; ++n) acc[a][b][m][n] = (f32x4){0.f, 0.f, 0.f, 0.f};
;         cur = nxt; cA = nA; cB = nB; ++ui;
;         if (wr == 1) PG8_BAR;
;     __device__ __forceinline__ void operator()(AccRef acc, const pg8::Unit& u, int wr, int wc, int fr, int fq) const {
;     ...
;             for (int m = 0; m < 4; ++m) { const size_t off = (size_t)(row0 + ai * 128 + m * 16) * 1024 + col0;
; #pragma unroll
;                 for (int bj = 0; bj < 2; ++bj) { const f32x4 x0 = __builtin_nontemporal_load((const f32x4*)(xb + off + bj * 32)), x1 = __builtin_nontemporal_load((const f32x4*)(xb + off + bj * 32 + 4));
;                     __builtin_nontemporal_store(x0 + acc[ai][bj][m][0], (f32x4*)(out + off + bj * 32)); __builtin_nontemporal_store(x1 + acc[ai][bj][m][1], (f32x4*)(out + off + bj * 32 + 4)); } }
	v_pk_add_f32 v[68:69], v[68:69], v[170:171]
	v_pk_add_f32 v[70:71], v[70:71], v[172:173]
	v_pk_add_f32 v[64:65], v[64:65], v[174:175]
	v_pk_add_f32 v[66:67], v[66:67], v[176:177]
	v_add_u32_e32 v139, 0x30000, v138
	global_store_dwordx4 v139, v[68:71], s[60:61] offset:128 nt
	global_store_dwordx4 v139, v[64:67], s[60:61] offset:144 nt
	v_add_u32_e32 v139, 0x90000, v138
	global_load_dwordx4 v[170:173], v139, s[26:27] offset:128 nt
	global_load_dwordx4 v[174:177], v139, s[26:27] offset:144 nt
	s_waitcnt vmcnt(12)
	v_pk_add_f32 v[60:61], v[60:61], v[146:147]
	v_pk_add_f32 v[62:63], v[62:63], v[148:149]
	v_pk_add_f32 v[56:57], v[56:57], v[150:151]
	v_pk_add_f32 v[58:59], v[58:59], v[152:153]
	v_add_u32_e32 v139, 0x80000, v138
	global_store_dwordx4 v139, v[60:63], s[60:61] nt
	global_store_dwordx4 v139, v[56:59], s[60:61] offset:16 nt
	v_add_u32_e32 v139, 0xa0000, v138
	global_load_dwordx4 v[146:149], v139, s[26:27] nt
	global_load_dwordx4 v[150:153], v139, s[26:27] offset:16 nt
	s_waitcnt vmcnt(12)
	v_pk_add_f32 v[48:49], v[48:49], v[154:155]
	v_pk_add_f32 v[50:51], v[50:51], v[156:157]
	v_pk_add_f32 v[44:45], v[44:45], v[158:159]
	v_pk_add_f32 v[46:47], v[46:47], v[160:161]
	v_add_u32_e32 v139, 0x80000, v138
	global_store_dwordx4 v139, v[48:51], s[60:61] offset:128 nt
	global_store_dwordx4 v139, v[44:47], s[60:61] offset:144 nt
	v_add_u32_e32 v139, 0xa0000, v138
	global_load_dwordx4 v[154:157], v139, s[26:27] offset:128 nt
	global_load_dwordx4 v[158:161], v139, s[26:27] offset:144 nt
	s_waitcnt vmcnt(12)
	v_pk_add_f32 v[52:53], v[52:53], v[162:163]
	v_pk_add_f32 v[54:55], v[54:55], v[164:165]
	v_pk_add_f32 v[40:41], v[40:41], v[166:167]
	v_pk_add_f32 v[42:43], v[42:43], v[168:169]
	v_add_u32_e32 v139, 0x90000, v138
	global_store_dwordx4 v139, v[52:55], s[60:61] nt
	global_store_dwordx4 v139, v[40:43], s[60:61] offset:16 nt
	v_add_u32_e32 v139, 0xb0000, v138
	global_load_dwordx4 v[162:165], v139, s[26:27] nt
	global_load_dwordx4 v[166:169], v139, s[26:27] offset:16 nt
	s_waitcnt vmcnt(12)
	v_pk_add_f32 v[32:33], v[32:33], v[170:171]
	v_pk_add_f32 v[34:35], v[34:35], v[172:173]
	v_pk_add_f32 v[28:29], v[28:29], v[174:175]
	v_pk_add_f32 v[30:31], v[30:31], v[176:177]
	v_add_u32_e32 v139, 0x90000, v138
	global_store_dwordx4 v139, v[32:35], s[60:61] offset:128 nt
	global_store_dwordx4 v139, v[28:31], s[60:61] offset:144 nt
	v_add_u32_e32 v139, 0xb0000, v138
	global_load_dwordx4 v[170:173], v139, s[26:27] offset:128 nt
	global_load_dwordx4 v[174:177], v139, s[26:27] offset:144 nt
	s_waitcnt vmcnt(12)
	v_pk_add_f32 v[36:37], v[36:37], v[146:147]
	v_pk_add_f32 v[38:39], v[38:39], v[148:149]
	v_pk_add_f32 v[24:25], v[24:25], v[150:151]
	v_pk_add_f32 v[26:27], v[26:27], v[152:153]
	v_add_u32_e32 v139, 0xa0000, v138
	global_store_dwordx4 v139, v[36:39], s[60:61] nt
	global_store_dwordx4 v139, v[24:27], s[60:61] offset:16 nt
	s_waitcnt vmcnt(10)
	v_pk_add_f32 v[16:17], v[16:17], v[154:155]
	v_pk_add_f32 v[18:19], v[18:19], v[156:157]
	v_pk_add_f32 v[12:13], v[12:13], v[158:159]
	v_pk_add_f32 v[14:15], v[14:15], v[160:161]
	v_add_u32_e32 v139, 0xa0000, v138
	global_store_dwordx4 v139, v[16:19], s[60:61] offset:128 nt
	global_store_dwordx4 v139, v[12:15], s[60:61] offset:144 nt
	s_waitcnt vmcnt(8)
	v_pk_add_f32 v[20:21], v[20:21], v[162:163]
	v_pk_add_f32 v[22:23], v[22:23], v[164:165]
	v_pk_add_f32 v[8:9], v[8:9], v[166:167]
	v_pk_add_f32 v[10:11], v[10:11], v[168:169]
	v_add_u32_e32 v139, 0xb0000, v138
	global_store_dwordx4 v139, v[20:23], s[60:61] nt
	global_store_dwordx4 v139, v[8:11], s[60:61] offset:16 nt
	s_waitcnt vmcnt(6)
	v_pk_add_f32 v[4:5], v[4:5], v[170:171]
	v_pk_add_f32 v[6:7], v[6:7], v[172:173]
	v_pk_add_f32 v[0:1], v[0:1], v[174:175]
	v_pk_add_f32 v[2:3], v[2:3], v[176:177]
	v_add_u32_e32 v139, 0xb0000, v138
	global_store_dwordx4 v139, v[4:7], s[60:61] offset:128 nt
	global_store_dwordx4 v139, v[0:3], s[60:61] offset:144 nt
	s_cbranch_vccnz .LBB0_594
	s_andn2_b64 vcc, exec, s[0:1]
	s_cbranch_vccnz .LBB0_593
	s_barrier
	s_branch .LBB0_593
